# hyena st0: spectrum-store drain no longer waited at the end of st0 (the st1 input-load waits cover it before the next barrier)
# speedup vs baseline: 1.2104x; 1.0018x over previous
; HD float2 cmul(float2 a, float2 b){ return make_float2(a.x*b.x - a.y*b.y, a.x*b.y + a.y*b.x); }
; HD int rev4_14(int p){ unsigned r = __brev((unsigned)p) >> 18; return (int)(((r & 0x2AAAu) >> 1) | ((r & 0x1555u) << 1)); }
; template<bool INV, int LQ, bool BARRIER=true>
; HD void fft_pass(float2* Z, const float2* twA, const float2* twB, int tid){
;     ...
;     int j=tid&(q-1); int base0=((tid>>LQ)<<(LQ+2))+j;
;     float2 w1=make_float2(1.f,0.f), w2=w1, w3=w1;
;     if (LQ>0){ int k=j*tws; w1=cmul(twA[k>>6],twB[k&63]); w2=cmul(w1,w1); w3=cmul(w2,w1); }
;     _Pragma("unroll") for (int i=0;i<8;++i){ int base=base0+i*2048; bf4c<INV,(LQ==0)>(Z,base,base+q,base+2*q,base+3*q,w1,w2,w3); }
;   }
;   if (BARRIER) __syncthreads(); else asm volatile("s_waitcnt lgkmcnt(0)" ::: "memory");
; __device__ __forceinline__ void phase_hyena(KP kp_, int hf){ asm volatile("" : "+s"(kp_)); const Params p=load_params(kp_);
;     ...
;         fft_pass<false,0>(Z,twA,twB,tid);
;     _Pragma("unroll 2") for (int i=0;i<8;++i){ int q0=(tid+512*i)*4; u32x4 h0w, h1w;
;       _Pragma("unroll") for (int m=0;m<4;++m){ int q=q0+m; int k=rev4_14(q);
;         float2 Fk=Z[q], Fn=Z[rev4_14((16384-k)&16383)];
;         f16x2 h0v={(_Float16)(0.5f*nrm0*(Fk.x+Fn.x)),(_Float16)(0.5f*nrm0*(Fk.y-Fn.y))};
.LBB0_1344:
	s_and_b64 vcc, exec, s[12:13]
	s_cbranch_vccz .LBB0_1198
	ds_read_b128 v[0:3], v203
	ds_read_b128 v[4:7], v203 offset:16
	s_mov_b32 s12, 0.5
	s_mov_b32 s13, -0.5
	s_waitcnt lgkmcnt(0)
	v_pk_add_f32 v[12:13], v[0:1], v[4:5]
	v_pk_add_f32 v[14:15], v[2:3], v[6:7]
	v_pk_add_f32 v[0:1], v[0:1], v[4:5] neg_lo:[0,1] neg_hi:[0,1]
	v_pk_add_f32 v[2:3], v[2:3], v[6:7] neg_lo:[0,1] neg_hi:[0,1]
	v_pk_add_f32 v[8:9], v[12:13], v[14:15]
	v_pk_add_f32 v[4:5], v[0:1], v[2:3] op_sel:[0,1] op_sel_hi:[1,0]
	v_pk_add_f32 v[2:3], v[0:1], v[2:3] op_sel:[0,1] op_sel_hi:[1,0] neg_lo:[0,1] neg_hi:[0,1]
	v_mov_b32_e32 v10, v4
	v_mov_b32_e32 v11, v3
	v_pk_add_f32 v[0:1], v[12:13], v[14:15] neg_lo:[0,1] neg_hi:[0,1]
	v_mov_b32_e32 v3, v5
	ds_write_b128 v203, v[8:11]
	ds_write_b128 v203, v[0:3] offset:16
	ds_read_b128 v[0:3], v203 offset:16384
	ds_read_b128 v[4:7], v203 offset:16400
	s_waitcnt lgkmcnt(0)
	v_pk_add_f32 v[12:13], v[0:1], v[4:5]
	v_pk_add_f32 v[14:15], v[2:3], v[6:7]
	v_pk_add_f32 v[0:1], v[0:1], v[4:5] neg_lo:[0,1] neg_hi:[0,1]
	v_pk_add_f32 v[2:3], v[2:3], v[6:7] neg_lo:[0,1] neg_hi:[0,1]
	v_pk_add_f32 v[8:9], v[12:13], v[14:15]
	v_pk_add_f32 v[4:5], v[0:1], v[2:3] op_sel:[0,1] op_sel_hi:[1,0]
	v_pk_add_f32 v[2:3], v[0:1], v[2:3] op_sel:[0,1] op_sel_hi:[1,0] neg_lo:[0,1] neg_hi:[0,1]
	v_mov_b32_e32 v10, v4
	v_mov_b32_e32 v11, v3
	v_pk_add_f32 v[0:1], v[12:13], v[14:15] neg_lo:[0,1] neg_hi:[0,1]
	v_mov_b32_e32 v3, v5
	ds_write_b128 v203, v[8:11] offset:16384
	ds_write_b128 v203, v[0:3] offset:16400
	ds_read_b128 v[0:3], v203 offset:32768
	ds_read_b128 v[4:7], v203 offset:32784
	s_waitcnt lgkmcnt(0)
	v_pk_add_f32 v[12:13], v[0:1], v[4:5]
	v_pk_add_f32 v[14:15], v[2:3], v[6:7]
	v_pk_add_f32 v[0:1], v[0:1], v[4:5] neg_lo:[0,1] neg_hi:[0,1]
	v_pk_add_f32 v[2:3], v[2:3], v[6:7] neg_lo:[0,1] neg_hi:[0,1]
	v_pk_add_f32 v[8:9], v[12:13], v[14:15]
	v_pk_add_f32 v[4:5], v[0:1], v[2:3] op_sel:[0,1] op_sel_hi:[1,0]
	v_pk_add_f32 v[2:3], v[0:1], v[2:3] op_sel:[0,1] op_sel_hi:[1,0] neg_lo:[0,1] neg_hi:[0,1]
	v_mov_b32_e32 v10, v4
	v_mov_b32_e32 v11, v3
	v_pk_add_f32 v[0:1], v[12:13], v[14:15] neg_lo:[0,1] neg_hi:[0,1]
	v_mov_b32_e32 v3, v5
	ds_write_b128 v203, v[8:11] offset:32768
	ds_write_b128 v203, v[0:3] offset:32784
	ds_read_b128 v[0:3], v203 offset:49152
	ds_read_b128 v[4:7], v203 offset:49168
	s_waitcnt lgkmcnt(0)
	v_pk_add_f32 v[12:13], v[0:1], v[4:5]
	v_pk_add_f32 v[14:15], v[2:3], v[6:7]
	v_pk_add_f32 v[0:1], v[0:1], v[4:5] neg_lo:[0,1] neg_hi:[0,1]
	v_pk_add_f32 v[2:3], v[2:3], v[6:7] neg_lo:[0,1] neg_hi:[0,1]
	v_pk_add_f32 v[8:9], v[12:13], v[14:15]
	v_pk_add_f32 v[4:5], v[0:1], v[2:3] op_sel:[0,1] op_sel_hi:[1,0]
	v_pk_add_f32 v[2:3], v[0:1], v[2:3] op_sel:[0,1] op_sel_hi:[1,0] neg_lo:[0,1] neg_hi:[0,1]
	v_mov_b32_e32 v10, v4
	v_mov_b32_e32 v11, v3
	v_pk_add_f32 v[0:1], v[12:13], v[14:15] neg_lo:[0,1] neg_hi:[0,1]
	v_mov_b32_e32 v3, v5
	ds_write_b128 v203, v[8:11] offset:49152
	ds_write_b128 v203, v[0:3] offset:49168
	ds_read_b128 v[0:3], v204
	ds_read_b128 v[4:7], v205
	s_waitcnt lgkmcnt(0)
	v_pk_add_f32 v[12:13], v[0:1], v[4:5]
	v_pk_add_f32 v[14:15], v[2:3], v[6:7]
	v_pk_add_f32 v[0:1], v[0:1], v[4:5] neg_lo:[0,1] neg_hi:[0,1]
	v_pk_add_f32 v[2:3], v[2:3], v[6:7] neg_lo:[0,1] neg_hi:[0,1]
	v_pk_add_f32 v[8:9], v[12:13], v[14:15]
	v_pk_add_f32 v[4:5], v[0:1], v[2:3] op_sel:[0,1] op_sel_hi:[1,0]
	v_pk_add_f32 v[2:3], v[0:1], v[2:3] op_sel:[0,1] op_sel_hi:[1,0] neg_lo:[0,1] neg_hi:[0,1]
	v_mov_b32_e32 v10, v4
	v_mov_b32_e32 v11, v3
	v_pk_add_f32 v[0:1], v[12:13], v[14:15] neg_lo:[0,1] neg_hi:[0,1]
	v_mov_b32_e32 v3, v5
	ds_write_b128 v204, v[8:11]
	ds_write_b128 v205, v[0:3]
	ds_read_b128 v[0:3], v206
	ds_read_b128 v[4:7], v207
	s_waitcnt lgkmcnt(0)
	v_pk_add_f32 v[12:13], v[0:1], v[4:5]
	v_pk_add_f32 v[14:15], v[2:3], v[6:7]
	v_pk_add_f32 v[0:1], v[0:1], v[4:5] neg_lo:[0,1] neg_hi:[0,1]
	v_pk_add_f32 v[2:3], v[2:3], v[6:7] neg_lo:[0,1] neg_hi:[0,1]
	v_pk_add_f32 v[8:9], v[12:13], v[14:15]
	v_pk_add_f32 v[4:5], v[0:1], v[2:3] op_sel:[0,1] op_sel_hi:[1,0]
	v_pk_add_f32 v[2:3], v[0:1], v[2:3] op_sel:[0,1] op_sel_hi:[1,0] neg_lo:[0,1] neg_hi:[0,1]
	v_mov_b32_e32 v10, v4
	v_mov_b32_e32 v11, v3
	v_pk_add_f32 v[0:1], v[12:13], v[14:15] neg_lo:[0,1] neg_hi:[0,1]
	v_mov_b32_e32 v3, v5
	ds_write_b128 v206, v[8:11]
	ds_write_b128 v207, v[0:3]
	ds_read_b128 v[0:3], v208
	ds_read_b128 v[4:7], v209
	s_waitcnt lgkmcnt(0)
	v_pk_add_f32 v[12:13], v[0:1], v[4:5]
	v_pk_add_f32 v[14:15], v[2:3], v[6:7]
	v_pk_add_f32 v[0:1], v[0:1], v[4:5] neg_lo:[0,1] neg_hi:[0,1]
	v_pk_add_f32 v[2:3], v[2:3], v[6:7] neg_lo:[0,1] neg_hi:[0,1]
	v_pk_add_f32 v[8:9], v[12:13], v[14:15]
	v_pk_add_f32 v[4:5], v[0:1], v[2:3] op_sel:[0,1] op_sel_hi:[1,0]
	v_pk_add_f32 v[2:3], v[0:1], v[2:3] op_sel:[0,1] op_sel_hi:[1,0] neg_lo:[0,1] neg_hi:[0,1]
	v_mov_b32_e32 v10, v4
	v_mov_b32_e32 v11, v3
	v_pk_add_f32 v[0:1], v[12:13], v[14:15] neg_lo:[0,1] neg_hi:[0,1]
	v_mov_b32_e32 v3, v5
	ds_write_b128 v208, v[8:11]
	ds_write_b128 v209, v[0:3]
	ds_read_b128 v[0:3], v210
	ds_read_b128 v[4:7], v211
	s_waitcnt lgkmcnt(0)
	v_pk_add_f32 v[12:13], v[0:1], v[4:5]
	v_pk_add_f32 v[14:15], v[2:3], v[6:7]
	v_pk_add_f32 v[0:1], v[0:1], v[4:5] neg_lo:[0,1] neg_hi:[0,1]
	v_pk_add_f32 v[2:3], v[2:3], v[6:7] neg_lo:[0,1] neg_hi:[0,1]
	v_pk_add_f32 v[8:9], v[12:13], v[14:15]
	v_pk_add_f32 v[4:5], v[0:1], v[2:3] op_sel:[0,1] op_sel_hi:[1,0]
	v_pk_add_f32 v[2:3], v[0:1], v[2:3] op_sel:[0,1] op_sel_hi:[1,0] neg_lo:[0,1] neg_hi:[0,1]
	v_pk_add_f32 v[0:1], v[12:13], v[14:15] neg_lo:[0,1] neg_hi:[0,1]
	v_mov_b32_e32 v11, v3
	v_mov_b32_e32 v3, v5
	v_mov_b32_e32 v10, v4
	ds_write_b128 v211, v[0:3]
	v_mul_f32_e32 v2, 0.5, v78
	v_pk_mul_f32 v[0:1], v[78:79], s[12:13] op_sel:[1,0]
	s_mov_b32 s12, 0
	v_mov_b32_e32 v3, v203
	ds_write_b128 v210, v[8:11]
	s_waitcnt lgkmcnt(0)
	s_barrier
; HD int rev4_14(int p){ unsigned r = __brev((unsigned)p) >> 18; return (int)(((r & 0x2AAAu) >> 1) | ((r & 0x1555u) << 1)); }
; __device__ __forceinline__ void phase_hyena(KP kp_, int hf){ asm volatile("" : "+s"(kp_)); const Params p=load_params(kp_);
;     ...
;     _Pragma("unroll 2") for (int i=0;i<8;++i){ int q0=(tid+512*i)*4; u32x4 h0w, h1w;
;       _Pragma("unroll") for (int m=0;m<4;++m){ int q=q0+m; int k=rev4_14(q);
;         float2 Fk=Z[q], Fn=Z[rev4_14((16384-k)&16383)];
;         f16x2 h0v={(_Float16)(0.5f*nrm0*(Fk.x+Fn.x)),(_Float16)(0.5f*nrm0*(Fk.y-Fn.y))};
;         f16x2 h1v={(_Float16)(0.5f*nrm1*(Fk.y+Fn.y)),(_Float16)(-0.5f*nrm1*(Fk.x-Fn.x))};
;         unsigned u0=__builtin_bit_cast(unsigned,h0v), u1=__builtin_bit_cast(unsigned,h1v);
;         h0w[m]=u0; h1w[m]=u1; }
;       *(u32x4*)(H0p+q0)=h0w; *(u32x4*)(H1p+q0)=h1w; }
	v_lshlrev_b32_e32 v70, 5, v154
	v_add_u32_e32 v71, 0x10000, v70
	v_lshlrev_b32_e32 v72, 4, v154
	v_cmp_eq_u32_e64 s[12:13], 0, v154
	v_mov_b32_e32 v68, v154
	v_bfrev_b32_e32 v66, v68
	v_lshrrev_b32_e32 v66, 20, v66
	v_and_b32_e32 v67, 0xaaa, v66
	v_and_b32_e32 v66, 0x555, v66
	v_lshrrev_b32_e32 v67, 1, v67
	v_lshl_or_b32 v69, v66, 1, v67
	v_sub_u32_e32 v69, 0x1000, v69
	v_and_b32_e32 v69, 0xfff, v69
	v_bfrev_b32_e32 v66, v69
	v_lshrrev_b32_e32 v66, 20, v66
	v_and_b32_e32 v67, 0xaaa, v66
	v_and_b32_e32 v66, 0x555, v66
	v_lshrrev_b32_e32 v67, 1, v67
	v_lshl_or_b32 v68, v66, 1, v67
	v_lshlrev_b32_e32 v73, 5, v68
	ds_read_b128 v[4:7], v70 offset:0
	ds_read_b128 v[8:11], v70 offset:16
	ds_read_b128 v[12:15], v73
	ds_read_b128 v[16:19], v73 offset:16
	v_add_u32_e32 v68, 0x200, v154
	v_bfrev_b32_e32 v66, v68
	v_lshrrev_b32_e32 v66, 20, v66
	v_and_b32_e32 v67, 0xaaa, v66
	v_and_b32_e32 v66, 0x555, v66
	v_lshrrev_b32_e32 v67, 1, v67
	v_lshl_or_b32 v69, v66, 1, v67
	v_sub_u32_e32 v69, 0x1000, v69
	v_and_b32_e32 v69, 0xfff, v69
	v_bfrev_b32_e32 v66, v69
	v_lshrrev_b32_e32 v66, 20, v66
	v_and_b32_e32 v67, 0xaaa, v66
	v_and_b32_e32 v66, 0x555, v66
	v_lshrrev_b32_e32 v67, 1, v67
	v_lshl_or_b32 v68, v66, 1, v67
	v_lshlrev_b32_e32 v73, 5, v68
	ds_read_b128 v[20:23], v70 offset:16384
	ds_read_b128 v[24:27], v70 offset:16400
	ds_read_b128 v[58:61], v73
	ds_read_b128 v[62:65], v73 offset:16
	s_waitcnt lgkmcnt(4)
	v_cndmask_b32_e64 v112, v18, v12, s[12:13]
	v_cndmask_b32_e64 v113, v19, v13, s[12:13]
	v_cndmask_b32_e64 v114, v16, v18, s[12:13]
	v_cndmask_b32_e64 v115, v17, v19, s[12:13]
	v_cndmask_b32_e64 v116, v14, v16, s[12:13]
	v_cndmask_b32_e64 v117, v15, v17, s[12:13]
	v_cndmask_b32_e64 v118, v12, v14, s[12:13]
	v_cndmask_b32_e64 v119, v13, v15, s[12:13]
	v_pk_add_f32 v[104:105], v[4:5], v[112:113]
	v_pk_add_f32 v[106:107], v[4:5], v[112:113] neg_lo:[0,1] neg_hi:[0,1]
	v_mul_f32_e32 v108, v2, v104
	v_mul_f32_e32 v109, v2, v107
	v_mul_f32_e32 v110, v0, v105
	v_mul_f32_e32 v111, v1, v106
	v_cvt_pk_f16_f32 v82, v108, v109
	v_cvt_pk_f16_f32 v120, v110, v111
	v_pk_add_f32 v[104:105], v[6:7], v[114:115]
	v_pk_add_f32 v[106:107], v[6:7], v[114:115] neg_lo:[0,1] neg_hi:[0,1]
	v_mul_f32_e32 v108, v2, v104
	v_mul_f32_e32 v109, v2, v107
	v_mul_f32_e32 v110, v0, v105
	v_mul_f32_e32 v111, v1, v106
	v_cvt_pk_f16_f32 v83, v108, v109
	v_cvt_pk_f16_f32 v121, v110, v111
	v_pk_add_f32 v[104:105], v[8:9], v[116:117]
	v_pk_add_f32 v[106:107], v[8:9], v[116:117] neg_lo:[0,1] neg_hi:[0,1]
	v_mul_f32_e32 v108, v2, v104
	v_mul_f32_e32 v109, v2, v107
	v_mul_f32_e32 v110, v0, v105
	v_mul_f32_e32 v111, v1, v106
	v_cvt_pk_f16_f32 v84, v108, v109
	v_cvt_pk_f16_f32 v122, v110, v111
	v_pk_add_f32 v[104:105], v[10:11], v[118:119]
	v_pk_add_f32 v[106:107], v[10:11], v[118:119] neg_lo:[0,1] neg_hi:[0,1]
	v_mul_f32_e32 v108, v2, v104
	v_mul_f32_e32 v109, v2, v107
	v_mul_f32_e32 v110, v0, v105
	v_mul_f32_e32 v111, v1, v106
	v_cvt_pk_f16_f32 v85, v108, v109
	v_cvt_pk_f16_f32 v123, v110, v111
	v_mov_b32_e32 v74, v72
	global_store_dwordx4 v74, v[82:85], s[76:77]
	global_store_dwordx4 v74, v[120:123], s[78:79]
	s_nop 1
	v_add_u32_e32 v68, 0x400, v154
	v_bfrev_b32_e32 v66, v68
	v_lshrrev_b32_e32 v66, 20, v66
	v_and_b32_e32 v67, 0xaaa, v66
	v_and_b32_e32 v66, 0x555, v66
	v_lshrrev_b32_e32 v67, 1, v67
	v_lshl_or_b32 v69, v66, 1, v67
	v_sub_u32_e32 v69, 0x1000, v69
	v_and_b32_e32 v69, 0xfff, v69
	v_bfrev_b32_e32 v66, v69
	v_lshrrev_b32_e32 v66, 20, v66
	v_and_b32_e32 v67, 0xaaa, v66
	v_and_b32_e32 v66, 0x555, v66
	v_lshrrev_b32_e32 v67, 1, v67
	v_lshl_or_b32 v68, v66, 1, v67
	v_lshlrev_b32_e32 v73, 5, v68
	ds_read_b128 v[4:7], v70 offset:32768
	ds_read_b128 v[8:11], v70 offset:32784
	ds_read_b128 v[12:15], v73
	ds_read_b128 v[16:19], v73 offset:16
	s_waitcnt lgkmcnt(4)
	v_pk_add_f32 v[104:105], v[20:21], v[64:65]
	v_pk_add_f32 v[106:107], v[20:21], v[64:65] neg_lo:[0,1] neg_hi:[0,1]
	v_mul_f32_e32 v108, v2, v104
	v_mul_f32_e32 v109, v2, v107
	v_mul_f32_e32 v110, v0, v105
	v_mul_f32_e32 v111, v1, v106
	v_cvt_pk_f16_f32 v82, v108, v109
	v_cvt_pk_f16_f32 v120, v110, v111
	v_pk_add_f32 v[104:105], v[22:23], v[62:63]
	v_pk_add_f32 v[106:107], v[22:23], v[62:63] neg_lo:[0,1] neg_hi:[0,1]
	v_mul_f32_e32 v108, v2, v104
	v_mul_f32_e32 v109, v2, v107
	v_mul_f32_e32 v110, v0, v105
	v_mul_f32_e32 v111, v1, v106
	v_cvt_pk_f16_f32 v83, v108, v109
	v_cvt_pk_f16_f32 v121, v110, v111
	v_pk_add_f32 v[104:105], v[24:25], v[60:61]
	v_pk_add_f32 v[106:107], v[24:25], v[60:61] neg_lo:[0,1] neg_hi:[0,1]
	v_mul_f32_e32 v108, v2, v104
	v_mul_f32_e32 v109, v2, v107
	v_mul_f32_e32 v110, v0, v105
	v_mul_f32_e32 v111, v1, v106
	v_cvt_pk_f16_f32 v84, v108, v109
	v_cvt_pk_f16_f32 v122, v110, v111
	v_pk_add_f32 v[104:105], v[26:27], v[58:59]
	v_pk_add_f32 v[106:107], v[26:27], v[58:59] neg_lo:[0,1] neg_hi:[0,1]
	v_mul_f32_e32 v108, v2, v104
	v_mul_f32_e32 v109, v2, v107
	v_mul_f32_e32 v110, v0, v105
	v_mul_f32_e32 v111, v1, v106
	v_cvt_pk_f16_f32 v85, v108, v109
	v_cvt_pk_f16_f32 v123, v110, v111
	v_add_u32_e32 v74, 0x2000, v72
	global_store_dwordx4 v74, v[82:85], s[76:77]
	global_store_dwordx4 v74, v[120:123], s[78:79]
	s_nop 1
	v_add_u32_e32 v68, 0x600, v154
	v_bfrev_b32_e32 v66, v68
	v_lshrrev_b32_e32 v66, 20, v66
	v_and_b32_e32 v67, 0xaaa, v66
	v_and_b32_e32 v66, 0x555, v66
	v_lshrrev_b32_e32 v67, 1, v67
	v_lshl_or_b32 v69, v66, 1, v67
	v_sub_u32_e32 v69, 0x1000, v69
	v_and_b32_e32 v69, 0xfff, v69
	v_bfrev_b32_e32 v66, v69
	v_lshrrev_b32_e32 v66, 20, v66
	v_and_b32_e32 v67, 0xaaa, v66
	v_and_b32_e32 v66, 0x555, v66
	v_lshrrev_b32_e32 v67, 1, v67
	v_lshl_or_b32 v68, v66, 1, v67
	v_lshlrev_b32_e32 v73, 5, v68
	ds_read_b128 v[20:23], v70 offset:49152
	ds_read_b128 v[24:27], v70 offset:49168
	ds_read_b128 v[58:61], v73
	ds_read_b128 v[62:65], v73 offset:16
	s_waitcnt lgkmcnt(4)
; HD int rev4_14(int p){ unsigned r = __brev((unsigned)p) >> 18; return (int)(((r & 0x2AAAu) >> 1) | ((r & 0x1555u) << 1)); }
; __device__ __forceinline__ void phase_hyena(KP kp_, int hf){ asm volatile("" : "+s"(kp_)); const Params p=load_params(kp_);
;     ...
;     _Pragma("unroll 2") for (int i=0;i<8;++i){ int q0=(tid+512*i)*4; u32x4 h0w, h1w;
;       _Pragma("unroll") for (int m=0;m<4;++m){ int q=q0+m; int k=rev4_14(q);
;         float2 Fk=Z[q], Fn=Z[rev4_14((16384-k)&16383)];
;         f16x2 h0v={(_Float16)(0.5f*nrm0*(Fk.x+Fn.x)),(_Float16)(0.5f*nrm0*(Fk.y-Fn.y))};
;         f16x2 h1v={(_Float16)(0.5f*nrm1*(Fk.y+Fn.y)),(_Float16)(-0.5f*nrm1*(Fk.x-Fn.x))};
;         unsigned u0=__builtin_bit_cast(unsigned,h0v), u1=__builtin_bit_cast(unsigned,h1v);
;         h0w[m]=u0; h1w[m]=u1; }
;       *(u32x4*)(H0p+q0)=h0w; *(u32x4*)(H1p+q0)=h1w; }
	v_pk_add_f32 v[104:105], v[4:5], v[18:19]
	v_pk_add_f32 v[106:107], v[4:5], v[18:19] neg_lo:[0,1] neg_hi:[0,1]
	v_mul_f32_e32 v108, v2, v104
	v_mul_f32_e32 v109, v2, v107
	v_mul_f32_e32 v110, v0, v105
	v_mul_f32_e32 v111, v1, v106
	v_cvt_pk_f16_f32 v82, v108, v109
	v_cvt_pk_f16_f32 v120, v110, v111
	v_pk_add_f32 v[104:105], v[6:7], v[16:17]
	v_pk_add_f32 v[106:107], v[6:7], v[16:17] neg_lo:[0,1] neg_hi:[0,1]
	v_mul_f32_e32 v108, v2, v104
	v_mul_f32_e32 v109, v2, v107
	v_mul_f32_e32 v110, v0, v105
	v_mul_f32_e32 v111, v1, v106
	v_cvt_pk_f16_f32 v83, v108, v109
	v_cvt_pk_f16_f32 v121, v110, v111
	v_pk_add_f32 v[104:105], v[8:9], v[14:15]
	v_pk_add_f32 v[106:107], v[8:9], v[14:15] neg_lo:[0,1] neg_hi:[0,1]
	v_mul_f32_e32 v108, v2, v104
	v_mul_f32_e32 v109, v2, v107
	v_mul_f32_e32 v110, v0, v105
	v_mul_f32_e32 v111, v1, v106
	v_cvt_pk_f16_f32 v84, v108, v109
	v_cvt_pk_f16_f32 v122, v110, v111
	v_pk_add_f32 v[104:105], v[10:11], v[12:13]
	v_pk_add_f32 v[106:107], v[10:11], v[12:13] neg_lo:[0,1] neg_hi:[0,1]
	v_mul_f32_e32 v108, v2, v104
	v_mul_f32_e32 v109, v2, v107
	v_mul_f32_e32 v110, v0, v105
	v_mul_f32_e32 v111, v1, v106
	v_cvt_pk_f16_f32 v85, v108, v109
	v_cvt_pk_f16_f32 v123, v110, v111
	v_add_u32_e32 v74, 0x4000, v72
	global_store_dwordx4 v74, v[82:85], s[76:77]
	global_store_dwordx4 v74, v[120:123], s[78:79]
	s_nop 1
	v_add_u32_e32 v68, 0x800, v154
	v_bfrev_b32_e32 v66, v68
	v_lshrrev_b32_e32 v66, 20, v66
	v_and_b32_e32 v67, 0xaaa, v66
	v_and_b32_e32 v66, 0x555, v66
	v_lshrrev_b32_e32 v67, 1, v67
	v_lshl_or_b32 v69, v66, 1, v67
	v_sub_u32_e32 v69, 0x1000, v69
	v_and_b32_e32 v69, 0xfff, v69
	v_bfrev_b32_e32 v66, v69
	v_lshrrev_b32_e32 v66, 20, v66
	v_and_b32_e32 v67, 0xaaa, v66
	v_and_b32_e32 v66, 0x555, v66
	v_lshrrev_b32_e32 v67, 1, v67
	v_lshl_or_b32 v68, v66, 1, v67
	v_lshlrev_b32_e32 v73, 5, v68
	ds_read_b128 v[4:7], v71 offset:0
	ds_read_b128 v[8:11], v71 offset:16
	ds_read_b128 v[12:15], v73
	ds_read_b128 v[16:19], v73 offset:16
	s_waitcnt lgkmcnt(4)
	v_pk_add_f32 v[104:105], v[20:21], v[64:65]
	v_pk_add_f32 v[106:107], v[20:21], v[64:65] neg_lo:[0,1] neg_hi:[0,1]
	v_mul_f32_e32 v108, v2, v104
	v_mul_f32_e32 v109, v2, v107
	v_mul_f32_e32 v110, v0, v105
	v_mul_f32_e32 v111, v1, v106
	v_cvt_pk_f16_f32 v82, v108, v109
	v_cvt_pk_f16_f32 v120, v110, v111
	v_pk_add_f32 v[104:105], v[22:23], v[62:63]
	v_pk_add_f32 v[106:107], v[22:23], v[62:63] neg_lo:[0,1] neg_hi:[0,1]
	v_mul_f32_e32 v108, v2, v104
	v_mul_f32_e32 v109, v2, v107
	v_mul_f32_e32 v110, v0, v105
	v_mul_f32_e32 v111, v1, v106
	v_cvt_pk_f16_f32 v83, v108, v109
	v_cvt_pk_f16_f32 v121, v110, v111
	v_pk_add_f32 v[104:105], v[24:25], v[60:61]
	v_pk_add_f32 v[106:107], v[24:25], v[60:61] neg_lo:[0,1] neg_hi:[0,1]
	v_mul_f32_e32 v108, v2, v104
	v_mul_f32_e32 v109, v2, v107
	v_mul_f32_e32 v110, v0, v105
	v_mul_f32_e32 v111, v1, v106
	v_cvt_pk_f16_f32 v84, v108, v109
	v_cvt_pk_f16_f32 v122, v110, v111
	v_pk_add_f32 v[104:105], v[26:27], v[58:59]
	v_pk_add_f32 v[106:107], v[26:27], v[58:59] neg_lo:[0,1] neg_hi:[0,1]
	v_mul_f32_e32 v108, v2, v104
	v_mul_f32_e32 v109, v2, v107
	v_mul_f32_e32 v110, v0, v105
	v_mul_f32_e32 v111, v1, v106
	v_cvt_pk_f16_f32 v85, v108, v109
	v_cvt_pk_f16_f32 v123, v110, v111
	v_add_u32_e32 v74, 0x6000, v72
	global_store_dwordx4 v74, v[82:85], s[76:77]
	global_store_dwordx4 v74, v[120:123], s[78:79]
	s_nop 1
	v_add_u32_e32 v68, 0xa00, v154
	v_bfrev_b32_e32 v66, v68
	v_lshrrev_b32_e32 v66, 20, v66
	v_and_b32_e32 v67, 0xaaa, v66
	v_and_b32_e32 v66, 0x555, v66
	v_lshrrev_b32_e32 v67, 1, v67
	v_lshl_or_b32 v69, v66, 1, v67
	v_sub_u32_e32 v69, 0x1000, v69
	v_and_b32_e32 v69, 0xfff, v69
	v_bfrev_b32_e32 v66, v69
	v_lshrrev_b32_e32 v66, 20, v66
	v_and_b32_e32 v67, 0xaaa, v66
	v_and_b32_e32 v66, 0x555, v66
	v_lshrrev_b32_e32 v67, 1, v67
	v_lshl_or_b32 v68, v66, 1, v67
	v_lshlrev_b32_e32 v73, 5, v68
	ds_read_b128 v[20:23], v71 offset:16384
	ds_read_b128 v[24:27], v71 offset:16400
	ds_read_b128 v[58:61], v73
	ds_read_b128 v[62:65], v73 offset:16
	s_waitcnt lgkmcnt(4)
	v_pk_add_f32 v[104:105], v[4:5], v[18:19]
	v_pk_add_f32 v[106:107], v[4:5], v[18:19] neg_lo:[0,1] neg_hi:[0,1]
	v_mul_f32_e32 v108, v2, v104
	v_mul_f32_e32 v109, v2, v107
	v_mul_f32_e32 v110, v0, v105
	v_mul_f32_e32 v111, v1, v106
	v_cvt_pk_f16_f32 v82, v108, v109
	v_cvt_pk_f16_f32 v120, v110, v111
	v_pk_add_f32 v[104:105], v[6:7], v[16:17]
	v_pk_add_f32 v[106:107], v[6:7], v[16:17] neg_lo:[0,1] neg_hi:[0,1]
	v_mul_f32_e32 v108, v2, v104
	v_mul_f32_e32 v109, v2, v107
	v_mul_f32_e32 v110, v0, v105
	v_mul_f32_e32 v111, v1, v106
	v_cvt_pk_f16_f32 v83, v108, v109
	v_cvt_pk_f16_f32 v121, v110, v111
	v_pk_add_f32 v[104:105], v[8:9], v[14:15]
	v_pk_add_f32 v[106:107], v[8:9], v[14:15] neg_lo:[0,1] neg_hi:[0,1]
	v_mul_f32_e32 v108, v2, v104
	v_mul_f32_e32 v109, v2, v107
	v_mul_f32_e32 v110, v0, v105
	v_mul_f32_e32 v111, v1, v106
	v_cvt_pk_f16_f32 v84, v108, v109
	v_cvt_pk_f16_f32 v122, v110, v111
	v_pk_add_f32 v[104:105], v[10:11], v[12:13]
	v_pk_add_f32 v[106:107], v[10:11], v[12:13] neg_lo:[0,1] neg_hi:[0,1]
	v_mul_f32_e32 v108, v2, v104
	v_mul_f32_e32 v109, v2, v107
	v_mul_f32_e32 v110, v0, v105
	v_mul_f32_e32 v111, v1, v106
	v_cvt_pk_f16_f32 v85, v108, v109
	v_cvt_pk_f16_f32 v123, v110, v111
	v_add_u32_e32 v74, 0x8000, v72
	global_store_dwordx4 v74, v[82:85], s[76:77]
	global_store_dwordx4 v74, v[120:123], s[78:79]
	s_nop 1
	v_add_u32_e32 v68, 0xc00, v154
	v_bfrev_b32_e32 v66, v68
	v_lshrrev_b32_e32 v66, 20, v66
	v_and_b32_e32 v67, 0xaaa, v66
	v_and_b32_e32 v66, 0x555, v66
	v_lshrrev_b32_e32 v67, 1, v67
	v_lshl_or_b32 v69, v66, 1, v67
	v_sub_u32_e32 v69, 0x1000, v69
	v_and_b32_e32 v69, 0xfff, v69
	v_bfrev_b32_e32 v66, v69
	v_lshrrev_b32_e32 v66, 20, v66
	v_and_b32_e32 v67, 0xaaa, v66
	v_and_b32_e32 v66, 0x555, v66
	v_lshrrev_b32_e32 v67, 1, v67
	v_lshl_or_b32 v68, v66, 1, v67
	v_lshlrev_b32_e32 v73, 5, v68
	ds_read_b128 v[4:7], v71 offset:32768
	ds_read_b128 v[8:11], v71 offset:32784
	ds_read_b128 v[12:15], v73
	ds_read_b128 v[16:19], v73 offset:16
	s_waitcnt lgkmcnt(4)
; HD int rev4_14(int p){ unsigned r = __brev((unsigned)p) >> 18; return (int)(((r & 0x2AAAu) >> 1) | ((r & 0x1555u) << 1)); }
; __device__ __forceinline__ void phase_hyena(KP kp_, int hf){ asm volatile("" : "+s"(kp_)); const Params p=load_params(kp_);
;     ...
;     _Pragma("unroll 2") for (int i=0;i<8;++i){ int q0=(tid+512*i)*4; u32x4 h0w, h1w;
;       _Pragma("unroll") for (int m=0;m<4;++m){ int q=q0+m; int k=rev4_14(q);
;         float2 Fk=Z[q], Fn=Z[rev4_14((16384-k)&16383)];
;         f16x2 h0v={(_Float16)(0.5f*nrm0*(Fk.x+Fn.x)),(_Float16)(0.5f*nrm0*(Fk.y-Fn.y))};
;         f16x2 h1v={(_Float16)(0.5f*nrm1*(Fk.y+Fn.y)),(_Float16)(-0.5f*nrm1*(Fk.x-Fn.x))};
;         unsigned u0=__builtin_bit_cast(unsigned,h0v), u1=__builtin_bit_cast(unsigned,h1v);
;         h0w[m]=u0; h1w[m]=u1; }
;       *(u32x4*)(H0p+q0)=h0w; *(u32x4*)(H1p+q0)=h1w; }
;         __builtin_amdgcn_fence(__ATOMIC_ACQUIRE, "agent");
	v_pk_add_f32 v[104:105], v[20:21], v[64:65]
	v_pk_add_f32 v[106:107], v[20:21], v[64:65] neg_lo:[0,1] neg_hi:[0,1]
	v_mul_f32_e32 v108, v2, v104
	v_mul_f32_e32 v109, v2, v107
	v_mul_f32_e32 v110, v0, v105
	v_mul_f32_e32 v111, v1, v106
	v_cvt_pk_f16_f32 v82, v108, v109
	v_cvt_pk_f16_f32 v120, v110, v111
	v_pk_add_f32 v[104:105], v[22:23], v[62:63]
	v_pk_add_f32 v[106:107], v[22:23], v[62:63] neg_lo:[0,1] neg_hi:[0,1]
	v_mul_f32_e32 v108, v2, v104
	v_mul_f32_e32 v109, v2, v107
	v_mul_f32_e32 v110, v0, v105
	v_mul_f32_e32 v111, v1, v106
	v_cvt_pk_f16_f32 v83, v108, v109
	v_cvt_pk_f16_f32 v121, v110, v111
	v_pk_add_f32 v[104:105], v[24:25], v[60:61]
	v_pk_add_f32 v[106:107], v[24:25], v[60:61] neg_lo:[0,1] neg_hi:[0,1]
	v_mul_f32_e32 v108, v2, v104
	v_mul_f32_e32 v109, v2, v107
	v_mul_f32_e32 v110, v0, v105
	v_mul_f32_e32 v111, v1, v106
	v_cvt_pk_f16_f32 v84, v108, v109
	v_cvt_pk_f16_f32 v122, v110, v111
	v_pk_add_f32 v[104:105], v[26:27], v[58:59]
	v_pk_add_f32 v[106:107], v[26:27], v[58:59] neg_lo:[0,1] neg_hi:[0,1]
	v_mul_f32_e32 v108, v2, v104
	v_mul_f32_e32 v109, v2, v107
	v_mul_f32_e32 v110, v0, v105
	v_mul_f32_e32 v111, v1, v106
	v_cvt_pk_f16_f32 v85, v108, v109
	v_cvt_pk_f16_f32 v123, v110, v111
	v_add_u32_e32 v74, 0xa000, v72
	global_store_dwordx4 v74, v[82:85], s[76:77]
	global_store_dwordx4 v74, v[120:123], s[78:79]
	s_nop 1
	v_add_u32_e32 v68, 0xe00, v154
	v_bfrev_b32_e32 v66, v68
	v_lshrrev_b32_e32 v66, 20, v66
	v_and_b32_e32 v67, 0xaaa, v66
	v_and_b32_e32 v66, 0x555, v66
	v_lshrrev_b32_e32 v67, 1, v67
	v_lshl_or_b32 v69, v66, 1, v67
	v_sub_u32_e32 v69, 0x1000, v69
	v_and_b32_e32 v69, 0xfff, v69
	v_bfrev_b32_e32 v66, v69
	v_lshrrev_b32_e32 v66, 20, v66
	v_and_b32_e32 v67, 0xaaa, v66
	v_and_b32_e32 v66, 0x555, v66
	v_lshrrev_b32_e32 v67, 1, v67
	v_lshl_or_b32 v68, v66, 1, v67
	v_lshlrev_b32_e32 v73, 5, v68
	ds_read_b128 v[20:23], v71 offset:49152
	ds_read_b128 v[24:27], v71 offset:49168
	ds_read_b128 v[58:61], v73
	ds_read_b128 v[62:65], v73 offset:16
	s_waitcnt lgkmcnt(4)
	v_pk_add_f32 v[104:105], v[4:5], v[18:19]
	v_pk_add_f32 v[106:107], v[4:5], v[18:19] neg_lo:[0,1] neg_hi:[0,1]
	v_mul_f32_e32 v108, v2, v104
	v_mul_f32_e32 v109, v2, v107
	v_mul_f32_e32 v110, v0, v105
	v_mul_f32_e32 v111, v1, v106
	v_cvt_pk_f16_f32 v82, v108, v109
	v_cvt_pk_f16_f32 v120, v110, v111
	v_pk_add_f32 v[104:105], v[6:7], v[16:17]
	v_pk_add_f32 v[106:107], v[6:7], v[16:17] neg_lo:[0,1] neg_hi:[0,1]
	v_mul_f32_e32 v108, v2, v104
	v_mul_f32_e32 v109, v2, v107
	v_mul_f32_e32 v110, v0, v105
	v_mul_f32_e32 v111, v1, v106
	v_cvt_pk_f16_f32 v83, v108, v109
	v_cvt_pk_f16_f32 v121, v110, v111
	v_pk_add_f32 v[104:105], v[8:9], v[14:15]
	v_pk_add_f32 v[106:107], v[8:9], v[14:15] neg_lo:[0,1] neg_hi:[0,1]
	v_mul_f32_e32 v108, v2, v104
	v_mul_f32_e32 v109, v2, v107
	v_mul_f32_e32 v110, v0, v105
	v_mul_f32_e32 v111, v1, v106
	v_cvt_pk_f16_f32 v84, v108, v109
	v_cvt_pk_f16_f32 v122, v110, v111
	v_pk_add_f32 v[104:105], v[10:11], v[12:13]
	v_pk_add_f32 v[106:107], v[10:11], v[12:13] neg_lo:[0,1] neg_hi:[0,1]
	v_mul_f32_e32 v108, v2, v104
	v_mul_f32_e32 v109, v2, v107
	v_mul_f32_e32 v110, v0, v105
	v_mul_f32_e32 v111, v1, v106
	v_cvt_pk_f16_f32 v85, v108, v109
	v_cvt_pk_f16_f32 v123, v110, v111
	v_add_u32_e32 v74, 0xc000, v72
	global_store_dwordx4 v74, v[82:85], s[76:77]
	global_store_dwordx4 v74, v[120:123], s[78:79]
	s_nop 1
	s_waitcnt lgkmcnt(0)
	v_pk_add_f32 v[104:105], v[20:21], v[64:65]
	v_pk_add_f32 v[106:107], v[20:21], v[64:65] neg_lo:[0,1] neg_hi:[0,1]
	v_mul_f32_e32 v108, v2, v104
	v_mul_f32_e32 v109, v2, v107
	v_mul_f32_e32 v110, v0, v105
	v_mul_f32_e32 v111, v1, v106
	v_cvt_pk_f16_f32 v82, v108, v109
	v_cvt_pk_f16_f32 v120, v110, v111
	v_pk_add_f32 v[104:105], v[22:23], v[62:63]
	v_pk_add_f32 v[106:107], v[22:23], v[62:63] neg_lo:[0,1] neg_hi:[0,1]
	v_mul_f32_e32 v108, v2, v104
	v_mul_f32_e32 v109, v2, v107
	v_mul_f32_e32 v110, v0, v105
	v_mul_f32_e32 v111, v1, v106
	v_cvt_pk_f16_f32 v83, v108, v109
	v_cvt_pk_f16_f32 v121, v110, v111
	v_pk_add_f32 v[104:105], v[24:25], v[60:61]
	v_pk_add_f32 v[106:107], v[24:25], v[60:61] neg_lo:[0,1] neg_hi:[0,1]
	v_mul_f32_e32 v108, v2, v104
	v_mul_f32_e32 v109, v2, v107
	v_mul_f32_e32 v110, v0, v105
	v_mul_f32_e32 v111, v1, v106
	v_cvt_pk_f16_f32 v84, v108, v109
	v_cvt_pk_f16_f32 v122, v110, v111
	v_pk_add_f32 v[104:105], v[26:27], v[58:59]
	v_pk_add_f32 v[106:107], v[26:27], v[58:59] neg_lo:[0,1] neg_hi:[0,1]
	v_mul_f32_e32 v108, v2, v104
	v_mul_f32_e32 v109, v2, v107
	v_mul_f32_e32 v110, v0, v105
	v_mul_f32_e32 v111, v1, v106
	v_cvt_pk_f16_f32 v85, v108, v109
	v_cvt_pk_f16_f32 v123, v110, v111
	v_add_u32_e32 v74, 0xe000, v72
	global_store_dwordx4 v74, v[82:85], s[76:77]
	global_store_dwordx4 v74, v[120:123], s[78:79]
	s_nop 1
	s_waitcnt lgkmcnt(0)
	s_branch .LBB0_1198
